# v21 + dil-combine: g_dil stashed in LDS once, per-row global reloads replaced by ds_read, store-inclusive vmcnt waits removed
# speedup vs baseline: 1.0101x; 1.0015x over previous
; __device__ __forceinline__ void dil_combine_load(float (&o)[16], float& rn, const bf16_t* p0, const bf16_t* p1, const bf16_t* xo, const float* lse0, const float* lse1, const float* lse2, int lane) {
;     const int h = lane >> 3, seg = lane & 7;
;     const float e0 = lse0[h], e1 = lse1[h], e2 = lse2[h], em = fmaxf(e0, fmaxf(e1, e2));
;     float w0 = __builtin_amdgcn_exp2f(e0 - em), w1 = __builtin_amdgcn_exp2f(e1 - em), w2 = __builtin_amdgcn_exp2f(e2 - em); const float wi = 1.0f / (w0 + w1 + w2); w0 *= wi; w1 *= wi; w2 *= wi;
;     const int off = h * 128 + seg * 16;
; __global__ void __launch_bounds__(NWAVES * 64, 2) mega_fwd(Params P) {
;     ...
;         { PH_IDS
;           const float* gdl = P.in[9] + l * 128;
;           for (int m = gw; m < TOK; m += 4 * NGW) { float o[4][16], rn[4];
; #pragma unroll
;               for (int j = 0; j < 4; ++j) { const int mm = m + j * NGW; dil_combine_load(o[j], rn[j], PART0 + (size_t)mm * 1024, PART1 + (size_t)mm * 1024, XB + (size_t)mm * DM + 1024, LSE + (size_t)mm * 8, LSE + (size_t)(TOK + mm) * 8, LSE + (size_t)(2 * TOK + mm) * 8, lane); }
; #pragma unroll
;               for (int j = 0; j < 4; ++j) { const int mm = m + j * NGW; dil_combine_store(o[j], rn[j], XB + (size_t)mm * DM + 1024, gdl, lane); } } }
.LBB0_407:
	s_or_b64 exec, exec, s[4:5]
	v_readlane_b32 s0, v251, 3
	v_readlane_b32 s1, v251, 4
	v_readlane_b32 s78, v249, 34
	s_andn2_b64 vcc, exec, s[0:1]
	s_waitcnt lgkmcnt(0)
	v_cndmask_b32_e64 v2, 0, 1, s[0:1]
	v_cmp_ne_u32_e64 s[2:3], 1, v2
	v_readlane_b32 s79, v249, 35
	s_mov_b64 s[6:7], 0x33800000
	v_writelane_b32 v255, s2, 8
	s_mov_b64 s[8:9], 0x39c00000
	s_mov_b64 s[12:13], 0x10800800
	v_writelane_b32 v255, s3, 9
	s_mov_b32 s3, 0xf800000
	s_mov_b64 s[14:15], 0x40000
	s_mov_b64 s[26:27], 0x1000000
	s_mov_b64 s[30:31], 0x2000000
	s_barrier
	v_mbcnt_lo_u32_b32 v0, -1, 0
	v_mbcnt_hi_u32_b32 v0, -1, v0
	s_cbranch_vccnz .LBB0_410
	v_readlane_b32 s0, v255, 24
	v_readlane_b32 s1, v255, 25
	v_readlane_b32 s40, v249, 18
	s_lshl_b64 s[0:1], s[0:1], 2
	v_readlane_b32 s42, v249, 20
	v_lshlrev_b32_e32 v4, 4, v0
	v_readlane_b32 s43, v249, 21
	s_add_u32 s0, s42, s0
	v_ashrrev_i32_e32 v2, 3, v0
	v_and_b32_e32 v8, 0x70, v4
	v_lshlrev_b32_e32 v0, 2, v0
	s_addc_u32 s1, s43, s1
	v_xor_b32_e32 v127, 4, v0
	v_xor_b32_e32 v145, 8, v0
	v_xor_b32_e32 v149, 16, v0
	v_lshlrev_b32_e32 v0, 2, v8
	v_ashrrev_i32_e32 v3, 31, v2
	v_lshl_add_u64 v[74:75], s[0:1], 0, v[0:1]
	global_load_dwordx4 v[12:15], v[74:75], off
	global_load_dwordx4 v[16:19], v[74:75], off offset:16
	global_load_dwordx4 v[20:23], v[74:75], off offset:32
	global_load_dwordx4 v[24:27], v[74:75], off offset:48
	v_mov_b32_e32 v74, v0
	s_waitcnt vmcnt(0)
	ds_write_b128 v74, v[12:15]
	ds_write_b128 v74, v[16:19] offset:16
	ds_write_b128 v74, v[20:23] offset:32
	ds_write_b128 v74, v[24:27] offset:48
	s_waitcnt lgkmcnt(0)
	v_readlane_b32 s0, v253, 42
	v_lshlrev_b64 v[6:7], 2, v[2:3]
	v_readlane_b32 s1, v253, 43
	v_lshl_or_b32 v2, v2, 7, v8
	v_ashrrev_i32_e32 v5, 31, v4
	v_lshl_add_u64 v[76:77], s[0:1], 0, v[6:7]
	v_readlane_b32 s0, v253, 44
	v_readlane_b32 s1, v253, 45
	v_ashrrev_i32_e32 v3, 31, v2
	v_lshlrev_b64 v[4:5], 1, v[4:5]
	v_lshl_add_u64 v[78:79], s[0:1], 0, v[6:7]
	v_readlane_b32 s0, v253, 46
	v_readlane_b32 s1, v253, 47
	v_lshlrev_b64 v[2:3], 1, v[2:3]
	v_readlane_b32 s52, v249, 30
	v_lshl_add_u64 v[80:81], s[0:1], 0, v[6:7]
	v_readlane_b32 s0, v253, 48
	v_readlane_b32 s1, v253, 49
	v_readlane_b32 s53, v249, 31
	v_readlane_b32 s54, v249, 32
	v_lshl_add_u64 v[82:83], s[0:1], 0, v[6:7]
	v_readlane_b32 s0, v253, 50
	v_readlane_b32 s1, v253, 51
	v_readlane_b32 s55, v249, 33
	v_readlane_b32 s54, v249, 60
	v_lshl_add_u64 v[84:85], s[0:1], 0, v[6:7]
	v_readlane_b32 s0, v253, 52
	v_readlane_b32 s1, v253, 53
	v_readlane_b32 s52, v249, 58
	v_readlane_b32 s55, v249, 61
	v_lshl_add_u64 v[86:87], s[0:1], 0, v[6:7]
	v_readlane_b32 s0, v253, 54
	v_readlane_b32 s1, v253, 55
	v_readlane_b32 s53, v249, 59
	v_readlane_b32 s2, v254, 18
	v_lshl_add_u64 v[88:89], s[0:1], 0, v[6:7]
	v_readlane_b32 s0, v253, 56
	v_readlane_b32 s1, v253, 57
	v_readlane_b32 s41, v249, 19
	v_readlane_b32 s44, v249, 22
	v_lshl_add_u64 v[90:91], s[0:1], 0, v[6:7]
	v_readlane_b32 s0, v253, 58
	v_readlane_b32 s1, v253, 59
	v_readlane_b32 s45, v249, 23
	v_readlane_b32 s46, v249, 24
	v_lshl_add_u64 v[92:93], s[0:1], 0, v[6:7]
	v_readlane_b32 s0, v253, 60
	v_readlane_b32 s1, v253, 61
	v_readlane_b32 s47, v249, 25
	v_readlane_b32 s48, v249, 26
	v_lshl_add_u64 v[94:95], s[0:1], 0, v[4:5]
	v_lshl_add_u64 v[96:97], s[0:1], 0, v[2:3]
	v_readlane_b32 s0, v253, 62
	v_readlane_b32 s1, v253, 63
	v_readlane_b32 s49, v249, 27
	v_readlane_b32 s50, v249, 28
	v_lshl_add_u64 v[98:99], s[0:1], 0, v[2:3]
	v_readlane_b32 s0, v254, 0
	v_readlane_b32 s1, v254, 1
	v_readlane_b32 s51, v249, 29
	s_nop 0
	v_lshl_add_u64 v[100:101], s[0:1], 0, v[6:7]
	v_readlane_b32 s0, v254, 2
	v_readlane_b32 s1, v254, 3
	s_nop 1
	v_lshl_add_u64 v[102:103], s[0:1], 0, v[4:5]
	v_lshl_add_u64 v[104:105], s[0:1], 0, v[2:3]
	v_readlane_b32 s0, v254, 4
	v_readlane_b32 s1, v254, 5
	s_nop 1
	v_lshl_add_u64 v[106:107], s[0:1], 0, v[2:3]
	v_readlane_b32 s0, v254, 6
	v_readlane_b32 s1, v254, 7
	s_nop 1
	v_lshl_add_u64 v[108:109], s[0:1], 0, v[6:7]
	v_readlane_b32 s0, v254, 8
	v_readlane_b32 s1, v254, 9
	s_nop 1
	v_lshl_add_u64 v[110:111], s[0:1], 0, v[4:5]
	v_lshl_add_u64 v[112:113], s[0:1], 0, v[2:3]
	v_readlane_b32 s0, v254, 10
	v_readlane_b32 s1, v254, 11
	s_nop 1
	v_lshl_add_u64 v[114:115], s[0:1], 0, v[2:3]
	v_readlane_b32 s0, v254, 12
	v_readlane_b32 s1, v254, 13
	s_nop 1
	v_lshl_add_u64 v[116:117], s[0:1], 0, v[6:7]
	v_readlane_b32 s0, v254, 14
	v_readlane_b32 s1, v254, 15
	s_nop 1
	v_lshl_add_u64 v[118:119], s[0:1], 0, v[4:5]
	v_lshl_add_u64 v[120:121], s[0:1], 0, v[2:3]
	v_readlane_b32 s0, v254, 16
	v_readlane_b32 s1, v254, 17
	s_nop 1
	v_lshl_add_u64 v[122:123], s[0:1], 0, v[2:3]
; __device__ __forceinline__ float bflo(unsigned w) { return __uint_as_float(w << 16); }
; __device__ __forceinline__ float bfhi(unsigned w) { return __uint_as_float(w & 0xffff0000u); }
; __device__ __forceinline__ void dil_combine_load(float (&o)[16], float& rn, const bf16_t* p0, const bf16_t* p1, const bf16_t* xo, const float* lse0, const float* lse1, const float* lse2, int lane) {
;     const int h = lane >> 3, seg = lane & 7;
;     const float e0 = lse0[h], e1 = lse1[h], e2 = lse2[h], em = fmaxf(e0, fmaxf(e1, e2));
;     float w0 = __builtin_amdgcn_exp2f(e0 - em), w1 = __builtin_amdgcn_exp2f(e1 - em), w2 = __builtin_amdgcn_exp2f(e2 - em); const float wi = 1.0f / (w0 + w1 + w2); w0 *= wi; w1 *= wi; w2 *= wi;
;     const int off = h * 128 + seg * 16;
;     float ss = 0.f;
; #pragma unroll
;     for (int j = 0; j < 2; ++j) { const u32x4 a = *(const u32x4*)(p0 + off + 8 * j), bq = *(const u32x4*)(p1 + off + 8 * j), cq = *(const u32x4*)(xo + off + 8 * j);
; #pragma unroll
;         for (int e = 0; e < 4; ++e) { o[8 * j + 2 * e] = w0 * bflo(a[e]) + w1 * bflo(bq[e]) + w2 * bflo(cq[e]); o[8 * j + 2 * e + 1] = w0 * bfhi(a[e]) + w1 * bfhi(bq[e]) + w2 * bfhi(cq[e]); } }
.LBB0_409:
	s_nop 0
	v_lshl_add_u64 v[2:3], s[76:77], 0, v[92:93]
	global_load_dword v0, v[2:3], off
	v_lshl_add_u64 v[2:3], s[76:77], 0, v[90:91]
	global_load_dword v4, v[2:3], off
	v_lshl_add_u64 v[2:3], s[76:77], 0, v[88:89]
	global_load_dword v2, v[2:3], off
	v_lshl_add_u64 v[12:13], s[76:77], 0, v[96:97]
	v_lshl_add_u64 v[14:15], v[12:13], 0, s[12:13]
	s_addk_i32 s2, 0x2000
	v_lshl_add_u64 v[88:89], v[88:89], 0, s[14:15]
	v_lshl_add_u64 v[90:91], v[90:91], 0, s[14:15]
	v_lshl_add_u64 v[92:93], v[92:93], 0, s[14:15]
	v_lshl_add_u64 v[96:97], v[96:97], 0, s[30:31]
	s_cmpk_gt_i32 s2, 0x5fff
	s_waitcnt vmcnt(0)
	v_max3_f32 v3, v0, v4, v2
	v_sub_f32_e32 v0, v0, v3
	v_exp_f32_e32 v219, v0
	v_sub_f32_e32 v0, v4, v3
	v_exp_f32_e32 v218, v0
	v_sub_f32_e32 v0, v2, v3
	v_exp_f32_e32 v0, v0
	v_add_f32_e32 v2, v219, v218
	v_add_f32_e32 v2, v0, v2
	v_div_scale_f32 v3, s[0:1], v2, v2, 1.0
	v_rcp_f32_e32 v4, v3
	s_nop 0
	v_fma_f32 v5, -v3, v4, 1.0
	v_fmac_f32_e32 v4, v5, v4
	v_div_scale_f32 v5, vcc, 1.0, v2, 1.0
	v_mul_f32_e32 v6, v5, v4
	v_fma_f32 v7, -v3, v6, v5
	v_fmac_f32_e32 v6, v7, v4
	v_fma_f32 v3, -v3, v6, v5
	v_div_fmas_f32 v3, v3, v4, v6
	v_lshl_add_u64 v[6:7], s[76:77], 0, v[98:99]
	v_div_fixup_f32 v220, v3, v2, 1.0
	v_add_co_u32_e32 v2, vcc, s21, v6
	v_lshl_add_u64 v[8:9], v[6:7], 0, s[6:7]
	s_nop 0
	v_addc_co_u32_e32 v3, vcc, 0, v7, vcc
	global_load_dwordx4 v[2:5], v[2:3], off
	s_nop 0
	global_load_dwordx4 v[58:61], v[8:9], off offset:16
	v_lshl_add_u64 v[10:11], v[6:7], 0, s[8:9]
	v_add_co_u32_e32 v6, vcc, s22, v6
	v_mul_f32_e32 v178, v0, v220
	s_nop 0
	v_addc_co_u32_e32 v7, vcc, 0, v7, vcc
	global_load_dwordx4 v[6:9], v[6:7], off
	s_nop 0
	global_load_dwordx4 v[62:65], v[10:11], off offset:16
	v_add_co_u32_e32 v10, vcc, s28, v12
	v_pk_mul_f32 v[218:219], v[218:219], v[220:221] op_sel_hi:[1,0]
	s_nop 0
	v_addc_co_u32_e32 v11, vcc, 0, v13, vcc
	global_load_dwordx4 v[54:57], v[10:11], off offset:2048
	global_load_dwordx4 v[50:53], v[14:15], off offset:16
	v_lshl_add_u64 v[12:13], s[76:77], 0, v[120:121]
	v_lshl_add_u64 v[14:15], v[12:13], 0, s[12:13]
	v_lshl_add_u64 v[98:99], v[98:99], 0, s[26:27]
	v_lshl_add_u64 v[120:121], v[120:121], 0, s[30:31]
	s_waitcnt vmcnt(5)
	v_lshlrev_b32_e32 v238, 16, v2
	v_and_b32_e32 v234, 0xffff0000, v2
	v_lshlrev_b32_e32 v241, 16, v3
	v_and_b32_e32 v237, 0xffff0000, v3
	v_lshl_add_u64 v[2:3], s[76:77], 0, v[116:117]
	global_load_dword v0, v[2:3], off
	v_lshl_add_u64 v[2:3], s[76:77], 0, v[86:87]
	v_lshlrev_b32_e32 v226, 16, v4
	v_and_b32_e32 v222, 0xffff0000, v4
	global_load_dword v4, v[2:3], off
	v_lshl_add_u64 v[2:3], s[76:77], 0, v[84:85]
	global_load_dword v2, v[2:3], off
	v_lshlrev_b32_e32 v229, 16, v5
	v_and_b32_e32 v225, 0xffff0000, v5
	s_waitcnt vmcnt(6)
	v_lshlrev_b32_e32 v240, 16, v6
	v_and_b32_e32 v236, 0xffff0000, v6
	v_lshlrev_b32_e32 v239, 16, v7
	v_and_b32_e32 v235, 0xffff0000, v7
	v_lshlrev_b32_e32 v228, 16, v8
	v_and_b32_e32 v224, 0xffff0000, v8
	v_lshlrev_b32_e32 v227, 16, v9
	v_and_b32_e32 v223, 0xffff0000, v9
	v_lshlrev_b32_e32 v217, 16, v59
	s_waitcnt vmcnt(5)
	v_lshlrev_b32_e32 v215, 16, v63
	v_and_b32_e32 v213, 0xffff0000, v59
	v_and_b32_e32 v211, 0xffff0000, v63
	v_lshlrev_b32_e32 v214, 16, v58
	v_and_b32_e32 v210, 0xffff0000, v58
	v_and_b32_e32 v184, 0xffff0000, v64
	v_lshlrev_b32_e32 v185, 16, v60
	s_waitcnt vmcnt(3)
	v_and_b32_e32 v186, 0xffff0000, v52
	v_lshlrev_b32_e32 v187, 16, v52
	v_pk_mul_f32 v[226:227], v[218:219], v[226:227] op_sel:[1,0] op_sel_hi:[0,1]
	v_pk_fma_f32 v[226:227], v[218:219], v[228:229], v[226:227]
	v_pk_mul_f32 v[222:223], v[218:219], v[222:223] op_sel:[1,0] op_sel_hi:[0,1]
	v_pk_fma_f32 v[222:223], v[218:219], v[224:225], v[222:223]
	v_lshlrev_b32_e32 v216, 16, v62
	v_pk_mul_f32 v[214:215], v[218:219], v[214:215] op_sel:[1,0] op_sel_hi:[0,1]
	v_and_b32_e32 v212, 0xffff0000, v62
	v_pk_fma_f32 v[214:215], v[218:219], v[216:217], v[214:215]
	v_pk_mul_f32 v[210:211], v[218:219], v[210:211] op_sel:[1,0] op_sel_hi:[0,1]
	v_pk_fma_f32 v[210:211], v[218:219], v[212:213], v[210:211]
	v_and_b32_e32 v52, 0xffff0000, v53
	v_lshlrev_b32_e32 v53, 16, v53
	v_lshl_add_u64 v[84:85], v[84:85], 0, s[14:15]
	v_lshl_add_u64 v[86:87], v[86:87], 0, s[14:15]
	v_lshl_add_u64 v[116:117], v[116:117], 0, s[14:15]
	s_waitcnt vmcnt(0)
	v_max3_f32 v3, v0, v4, v2
	v_sub_f32_e32 v0, v0, v3
	v_exp_f32_e32 v207, v0
	v_sub_f32_e32 v0, v4, v3
	v_exp_f32_e32 v206, v0
	v_sub_f32_e32 v0, v2, v3
	v_exp_f32_e32 v0, v0
	v_add_f32_e32 v2, v207, v206
	v_add_f32_e32 v2, v0, v2
	v_div_scale_f32 v3, s[0:1], v2, v2, 1.0
	v_rcp_f32_e32 v4, v3
	s_nop 0
	v_fma_f32 v5, -v3, v4, 1.0
	v_fmac_f32_e32 v4, v5, v4
	v_div_scale_f32 v5, vcc, 1.0, v2, 1.0
	v_mul_f32_e32 v6, v5, v4
	v_fma_f32 v7, -v3, v6, v5
	v_fmac_f32_e32 v6, v7, v4
	v_fma_f32 v3, -v3, v6, v5
	v_div_fmas_f32 v3, v3, v4, v6
	v_lshl_add_u64 v[6:7], s[76:77], 0, v[122:123]
	v_div_fixup_f32 v208, v3, v2, 1.0
	v_add_co_u32_e32 v2, vcc, s21, v6
	v_lshl_add_u64 v[8:9], v[6:7], 0, s[6:7]
	s_nop 0
	v_addc_co_u32_e32 v3, vcc, 0, v7, vcc
	global_load_dwordx4 v[2:5], v[2:3], off
	s_nop 0
	global_load_dwordx4 v[42:45], v[8:9], off offset:16
	v_lshl_add_u64 v[10:11], v[6:7], 0, s[8:9]
	v_add_co_u32_e32 v6, vcc, s22, v6
	v_mul_f32_e32 v144, v0, v208
	s_nop 0
	v_addc_co_u32_e32 v7, vcc, 0, v7, vcc
	global_load_dwordx4 v[6:9], v[6:7], off
	s_nop 0
	global_load_dwordx4 v[46:49], v[10:11], off offset:16
	v_add_co_u32_e32 v10, vcc, s28, v12
	v_lshl_add_u64 v[122:123], v[122:123], 0, s[26:27]
	s_nop 0
	v_addc_co_u32_e32 v11, vcc, 0, v13, vcc
	global_load_dwordx4 v[38:41], v[10:11], off offset:2048
	global_load_dwordx4 v[34:37], v[14:15], off offset:16
	v_lshl_add_u64 v[12:13], s[76:77], 0, v[112:113]
	v_lshl_add_u64 v[14:15], v[12:13], 0, s[12:13]
	v_lshl_add_u64 v[112:113], v[112:113], 0, s[30:31]
	s_waitcnt vmcnt(5)
; __device__ __forceinline__ float bflo(unsigned w) { return __uint_as_float(w << 16); }
; __device__ __forceinline__ float bfhi(unsigned w) { return __uint_as_float(w & 0xffff0000u); }
; __device__ __forceinline__ void dil_combine_load(float (&o)[16], float& rn, const bf16_t* p0, const bf16_t* p1, const bf16_t* xo, const float* lse0, const float* lse1, const float* lse2, int lane) {
;     const int h = lane >> 3, seg = lane & 7;
;     const float e0 = lse0[h], e1 = lse1[h], e2 = lse2[h], em = fmaxf(e0, fmaxf(e1, e2));
;     float w0 = __builtin_amdgcn_exp2f(e0 - em), w1 = __builtin_amdgcn_exp2f(e1 - em), w2 = __builtin_amdgcn_exp2f(e2 - em); const float wi = 1.0f / (w0 + w1 + w2); w0 *= wi; w1 *= wi; w2 *= wi;
;     const int off = h * 128 + seg * 16;
;     float ss = 0.f;
; #pragma unroll
;     for (int j = 0; j < 2; ++j) { const u32x4 a = *(const u32x4*)(p0 + off + 8 * j), bq = *(const u32x4*)(p1 + off + 8 * j), cq = *(const u32x4*)(xo + off + 8 * j);
; #pragma unroll
;         for (int e = 0; e < 4; ++e) { o[8 * j + 2 * e] = w0 * bflo(a[e]) + w1 * bflo(bq[e]) + w2 * bflo(cq[e]); o[8 * j + 2 * e + 1] = w0 * bfhi(a[e]) + w1 * bfhi(bq[e]) + w2 * bfhi(cq[e]); } }
	v_lshlrev_b32_e32 v230, 16, v2
	v_and_b32_e32 v202, 0xffff0000, v2
	v_lshlrev_b32_e32 v233, 16, v3
	v_and_b32_e32 v205, 0xffff0000, v3
	v_lshl_add_u64 v[2:3], s[76:77], 0, v[108:109]
	global_load_dword v0, v[2:3], off
	v_lshl_add_u64 v[2:3], s[76:77], 0, v[82:83]
	v_lshlrev_b32_e32 v174, 16, v4
	v_and_b32_e32 v170, 0xffff0000, v4
	global_load_dword v4, v[2:3], off
	v_lshl_add_u64 v[2:3], s[76:77], 0, v[80:81]
	global_load_dword v2, v[2:3], off
	v_lshlrev_b32_e32 v177, 16, v5
	v_and_b32_e32 v173, 0xffff0000, v5
	s_waitcnt vmcnt(6)
	v_lshlrev_b32_e32 v232, 16, v6
	v_and_b32_e32 v204, 0xffff0000, v6
	v_lshlrev_b32_e32 v231, 16, v7
	v_and_b32_e32 v203, 0xffff0000, v7
	v_lshlrev_b32_e32 v176, 16, v8
	v_and_b32_e32 v172, 0xffff0000, v8
	v_lshlrev_b32_e32 v175, 16, v9
	v_and_b32_e32 v171, 0xffff0000, v9
	v_lshlrev_b32_e32 v166, 16, v42
	v_and_b32_e32 v162, 0xffff0000, v42
	s_waitcnt vmcnt(5)
	v_lshlrev_b32_e32 v167, 16, v47
	v_and_b32_e32 v163, 0xffff0000, v47
	v_lshlrev_b32_e32 v169, 16, v43
	v_and_b32_e32 v165, 0xffff0000, v43
	v_lshlrev_b32_e32 v168, 16, v46
	v_and_b32_e32 v164, 0xffff0000, v46
	v_lshl_add_u64 v[80:81], v[80:81], 0, s[14:15]
	v_lshl_add_u64 v[82:83], v[82:83], 0, s[14:15]
	v_lshl_add_u64 v[108:109], v[108:109], 0, s[14:15]
	s_waitcnt vmcnt(0)
	v_max3_f32 v3, v0, v4, v2
	v_sub_f32_e32 v0, v0, v3
	v_exp_f32_e32 v147, v0
	v_sub_f32_e32 v0, v4, v3
	v_exp_f32_e32 v146, v0
	v_sub_f32_e32 v0, v2, v3
	v_exp_f32_e32 v0, v0
	v_add_f32_e32 v2, v147, v146
	v_add_f32_e32 v2, v0, v2
	v_div_scale_f32 v3, s[0:1], v2, v2, 1.0
	v_rcp_f32_e32 v4, v3
	s_nop 0
	v_fma_f32 v5, -v3, v4, 1.0
	v_fmac_f32_e32 v4, v5, v4
	v_div_scale_f32 v5, vcc, 1.0, v2, 1.0
	v_mul_f32_e32 v6, v5, v4
	v_fma_f32 v7, -v3, v6, v5
	v_fmac_f32_e32 v6, v7, v4
	v_fma_f32 v3, -v3, v6, v5
	v_div_fmas_f32 v3, v3, v4, v6
	v_lshl_add_u64 v[6:7], s[76:77], 0, v[114:115]
	v_div_fixup_f32 v148, v3, v2, 1.0
	v_add_co_u32_e32 v2, vcc, s21, v6
	v_lshl_add_u64 v[8:9], v[6:7], 0, s[6:7]
	s_nop 0
	v_addc_co_u32_e32 v3, vcc, 0, v7, vcc
	global_load_dwordx4 v[2:5], v[2:3], off
	s_nop 0
	global_load_dwordx4 v[26:29], v[8:9], off offset:16
	v_lshl_add_u64 v[10:11], v[6:7], 0, s[8:9]
	v_add_co_u32_e32 v6, vcc, s22, v6
	v_mul_f32_e32 v42, v0, v148
	s_nop 0
	v_addc_co_u32_e32 v7, vcc, 0, v7, vcc
	global_load_dwordx4 v[6:9], v[6:7], off
	s_nop 0
	global_load_dwordx4 v[30:33], v[10:11], off offset:16
	v_add_co_u32_e32 v10, vcc, s28, v12
	v_lshl_add_u64 v[114:115], v[114:115], 0, s[26:27]
	s_nop 0
	v_addc_co_u32_e32 v11, vcc, 0, v13, vcc
	global_load_dwordx4 v[22:25], v[10:11], off offset:2048
	global_load_dwordx4 v[18:21], v[14:15], off offset:16
	v_lshl_add_u64 v[14:15], s[76:77], 0, v[104:105]
	v_lshl_add_u64 v[104:105], v[104:105], 0, s[30:31]
	s_waitcnt vmcnt(5)
	v_lshlrev_b32_e32 v198, 16, v2
	v_and_b32_e32 v150, 0xffff0000, v2
	v_lshlrev_b32_e32 v201, 16, v3
	v_and_b32_e32 v153, 0xffff0000, v3
	v_lshl_add_u64 v[2:3], s[76:77], 0, v[100:101]
	global_load_dword v0, v[2:3], off
	v_lshl_add_u64 v[2:3], s[76:77], 0, v[78:79]
	v_lshlrev_b32_e32 v140, 16, v4
	v_and_b32_e32 v136, 0xffff0000, v4
	global_load_dword v4, v[2:3], off
	v_lshl_add_u64 v[2:3], s[76:77], 0, v[76:77]
	global_load_dword v2, v[2:3], off
	v_lshlrev_b32_e32 v143, 16, v5
	v_and_b32_e32 v139, 0xffff0000, v5
	s_waitcnt vmcnt(6)
	v_lshlrev_b32_e32 v200, 16, v6
	v_and_b32_e32 v152, 0xffff0000, v6
	v_lshlrev_b32_e32 v199, 16, v7
	v_and_b32_e32 v151, 0xffff0000, v7
	v_lshlrev_b32_e32 v142, 16, v8
	v_and_b32_e32 v138, 0xffff0000, v8
	v_lshlrev_b32_e32 v141, 16, v9
	v_and_b32_e32 v137, 0xffff0000, v9
	v_lshlrev_b32_e32 v132, 16, v26
	v_and_b32_e32 v128, 0xffff0000, v26
	v_lshlrev_b32_e32 v135, 16, v27
	s_waitcnt vmcnt(5)
	v_lshlrev_b32_e32 v133, 16, v31
	v_and_b32_e32 v131, 0xffff0000, v27
	v_and_b32_e32 v129, 0xffff0000, v31
	v_lshl_add_u64 v[26:27], v[14:15], 0, s[12:13]
	v_lshlrev_b32_e32 v134, 16, v30
	v_and_b32_e32 v130, 0xffff0000, v30
	v_lshl_add_u64 v[76:77], v[76:77], 0, s[14:15]
	v_lshl_add_u64 v[78:79], v[78:79], 0, s[14:15]
	v_lshl_add_u64 v[100:101], v[100:101], 0, s[14:15]
	s_waitcnt vmcnt(0)
	v_max3_f32 v3, v0, v4, v2
	v_sub_f32_e32 v0, v0, v3
	v_exp_f32_e32 v125, v0
	v_sub_f32_e32 v0, v4, v3
	v_exp_f32_e32 v124, v0
	v_sub_f32_e32 v0, v2, v3
	v_exp_f32_e32 v0, v0
	v_add_f32_e32 v2, v125, v124
	v_add_f32_e32 v2, v0, v2
	v_div_scale_f32 v3, s[0:1], v2, v2, 1.0
	v_rcp_f32_e32 v4, v3
	s_nop 0
	v_fma_f32 v5, -v3, v4, 1.0
	v_fmac_f32_e32 v4, v5, v4
	v_div_scale_f32 v5, vcc, 1.0, v2, 1.0
	v_mul_f32_e32 v6, v5, v4
	v_fma_f32 v7, -v3, v6, v5
	v_fmac_f32_e32 v6, v7, v4
	v_fma_f32 v3, -v3, v6, v5
	v_div_fmas_f32 v3, v3, v4, v6
	v_div_fixup_f32 v126, v3, v2, 1.0
	v_lshl_add_u64 v[2:3], s[76:77], 0, v[106:107]
	v_add_co_u32_e32 v6, vcc, s21, v2
	v_lshl_add_u64 v[4:5], v[2:3], 0, s[6:7]
	s_nop 0
	v_addc_co_u32_e32 v7, vcc, 0, v3, vcc
	v_lshl_add_u64 v[10:11], v[2:3], 0, s[8:9]
	v_add_co_u32_e32 v2, vcc, s22, v2
	global_load_dwordx4 v[66:69], v[6:7], off
	s_nop 0
	global_load_dwordx4 v[6:9], v[4:5], off offset:16
	v_addc_co_u32_e32 v3, vcc, 0, v3, vcc
	global_load_dwordx4 v[70:73], v[2:3], off
	s_nop 0
	global_load_dwordx4 v[10:13], v[10:11], off offset:16
	v_add_co_u32_e32 v2, vcc, s28, v14
	v_mul_f32_e32 v0, v0, v126
	s_nop 0
	v_addc_co_u32_e32 v3, vcc, 0, v15, vcc
	global_load_dwordx4 v[14:17], v[2:3], off offset:2048
	s_nop 0
	global_load_dwordx4 v[2:5], v[26:27], off offset:16
	v_lshl_add_u64 v[106:107], v[106:107], 0, s[26:27]
	s_waitcnt vmcnt(5)
	v_lshlrev_b32_e32 v158, 16, v66
	v_and_b32_e32 v154, 0xffff0000, v66
	v_lshlrev_b32_e32 v59, 16, v69
	s_waitcnt vmcnt(3)
; __device__ __forceinline__ float sx(float v, int mask, int lane) { return __int_as_float(__builtin_amdgcn_ds_bpermute((lane ^ mask) << 2, __float_as_int(v))); }
; __device__ __forceinline__ float bflo(unsigned w) { return __uint_as_float(w << 16); }
; __device__ __forceinline__ float bfhi(unsigned w) { return __uint_as_float(w & 0xffff0000u); }
; __device__ __forceinline__ unsigned pk2(float lo, float hi) { return f2bf(lo) | (f2bf(hi) << 16); }
; __device__ __forceinline__ void dil_combine_load(float (&o)[16], float& rn, const bf16_t* p0, const bf16_t* p1, const bf16_t* xo, const float* lse0, const float* lse1, const float* lse2, int lane) {
;     ...
;     for (int j = 0; j < 2; ++j) { const u32x4 a = *(const u32x4*)(p0 + off + 8 * j), bq = *(const u32x4*)(p1 + off + 8 * j), cq = *(const u32x4*)(xo + off + 8 * j);
; #pragma unroll
;         for (int e = 0; e < 4; ++e) { o[8 * j + 2 * e] = w0 * bflo(a[e]) + w1 * bflo(bq[e]) + w2 * bflo(cq[e]); o[8 * j + 2 * e + 1] = w0 * bfhi(a[e]) + w1 * bfhi(bq[e]) + w2 * bfhi(cq[e]); } }
; #pragma unroll
;     for (int d = 0; d < 16; ++d) ss += o[d] * o[d];
;     ss += sx(ss, 1, lane); ss += sx(ss, 2, lane); ss += sx(ss, 4, lane);
;     rn = 1.0f / sqrtf(ss * (1.f / 128.f) + RMS_EPS);
; }
; __device__ __forceinline__ void dil_combine_store(const float (&o)[16], float rn, bf16_t* xo, const float* g_dil, int lane) {
;     const int h = lane >> 3, seg = lane & 7; const int off = h * 128 + seg * 16;
; #pragma unroll
;     for (int j = 0; j < 2; ++j) { u32x4 w;
; #pragma unroll
;         for (int e = 0; e < 4; ++e) w[e] = pk2(o[8 * j + 2 * e] * rn * g_dil[seg * 16 + 8 * j + 2 * e], o[8 * j + 2 * e + 1] * rn * g_dil[seg * 16 + 8 * j + 2 * e + 1]);
;         *(u32x4*)(xo + off + 8 * j) = w; }
	v_lshlrev_b32_e32 v160, 16, v70
	v_and_b32_e32 v156, 0xffff0000, v70
	v_and_b32_e32 v31, 0xffff0000, v69
	s_waitcnt vmcnt(2)
	v_lshlrev_b32_e32 v70, 16, v10
	v_and_b32_e32 v66, 0xffff0000, v10
	v_lshlrev_b32_e32 v69, 16, v11
	v_and_b32_e32 v63, 0xffff0000, v11
	v_pk_mul_f32 v[10:11], v[218:219], v[238:239] op_sel:[1,0] op_sel_hi:[0,1]
	v_lshlrev_b32_e32 v58, 16, v72
	v_and_b32_e32 v30, 0xffff0000, v72
	v_lshlrev_b32_e32 v47, 16, v73
	v_and_b32_e32 v27, 0xffff0000, v73
	v_pk_fma_f32 v[10:11], v[218:219], v[240:241], v[10:11]
	v_lshlrev_b32_e32 v73, 16, v55
	v_lshlrev_b32_e32 v72, 16, v54
	v_pk_fma_f32 v[10:11], v[178:179], v[72:73], v[10:11] op_sel_hi:[0,1,1]
	v_pk_mul_f32 v[72:73], v[218:219], v[234:235] op_sel:[1,0] op_sel_hi:[0,1]
	v_pk_fma_f32 v[72:73], v[218:219], v[236:237], v[72:73]
	v_and_b32_e32 v55, 0xffff0000, v55
	v_and_b32_e32 v54, 0xffff0000, v54
	v_pk_fma_f32 v[54:55], v[178:179], v[54:55], v[72:73] op_sel_hi:[0,1,1]
	v_and_b32_e32 v72, 0xffff0000, v60
	v_lshlrev_b32_e32 v73, 16, v64
	v_pk_mul_f32 v[72:73], v[218:219], v[72:73] op_sel:[1,0] op_sel_hi:[0,1]
	v_pk_fma_f32 v[72:73], v[218:219], v[184:185], v[72:73]
	v_and_b32_e32 v184, 0xffff0000, v61
	v_lshlrev_b32_e32 v185, 16, v65
	v_pk_fma_f32 v[72:73], v[178:179], v[186:187], v[72:73] op_sel_hi:[0,1,1]
	v_and_b32_e32 v60, 0xffff0000, v65
	v_pk_mul_f32 v[64:65], v[218:219], v[184:185] op_sel:[1,0] op_sel_hi:[0,1]
	ds_read_b128 v[184:187], v74 offset:16
	ds_read_b128 v[234:237], v74
	v_pk_mul_f32 v[194:195], v[10:11], v[10:11]
	v_pk_mul_f32 v[196:197], v[54:55], v[54:55]
	v_lshlrev_b32_e32 v61, 16, v61
	v_pk_fma_f32 v[60:61], v[218:219], v[60:61], v[64:65]
	v_add_f32_e32 v43, v194, v196
	v_add_f32_e32 v43, v195, v43
	v_add_f32_e32 v43, v197, v43
	v_pk_mul_f32 v[220:221], v[72:73], v[72:73]
	v_pk_fma_f32 v[60:61], v[178:179], v[52:53], v[60:61] op_sel_hi:[0,1,1]
	v_pk_mul_f32 v[52:53], v[60:61], v[60:61]
	v_lshlrev_b32_e32 v161, 16, v67
	v_lshlrev_b32_e32 v159, 16, v71
	v_and_b32_e32 v157, 0xffff0000, v67
	v_and_b32_e32 v155, 0xffff0000, v71
	v_lshlrev_b32_e32 v46, 16, v68
	v_and_b32_e32 v26, 0xffff0000, v68
	v_lshlrev_b32_e32 v68, 16, v6
	v_and_b32_e32 v62, 0xffff0000, v6
	v_lshlrev_b32_e32 v71, 16, v7
	v_and_b32_e32 v67, 0xffff0000, v7
	v_lshl_add_u64 v[6:7], s[76:77], 0, v[94:95]
	v_lshl_add_u64 v[94:95], v[94:95], 0, s[30:31]
	s_waitcnt vmcnt(0) lgkmcnt(0)
	v_mov_b32_e32 v228, v184
	s_waitcnt lgkmcnt(0)
	v_mov_b32_e32 v64, v234
	v_mov_b32_e32 v65, v236
	v_mov_b32_e32 v236, v235
	v_lshlrev_b32_e32 v235, 16, v57
	v_lshlrev_b32_e32 v234, 16, v56
	v_and_b32_e32 v57, 0xffff0000, v57
	v_and_b32_e32 v56, 0xffff0000, v56
	v_pk_fma_f32 v[226:227], v[178:179], v[234:235], v[226:227] op_sel_hi:[0,1,1]
	v_pk_fma_f32 v[56:57], v[178:179], v[56:57], v[222:223] op_sel_hi:[0,1,1]
	v_pk_mul_f32 v[222:223], v[226:227], v[226:227]
	v_pk_mul_f32 v[224:225], v[56:57], v[56:57]
	v_add_f32_e32 v43, v222, v43
	v_mov_b32_e32 v229, v186
	v_mov_b32_e32 v186, v185
	v_lshlrev_b32_e32 v185, 16, v51
	v_lshlrev_b32_e32 v184, 16, v50
	v_add_f32_e32 v43, v224, v43
	v_and_b32_e32 v51, 0xffff0000, v51
	v_and_b32_e32 v50, 0xffff0000, v50
	v_pk_fma_f32 v[184:185], v[178:179], v[184:185], v[214:215] op_sel_hi:[0,1,1]
	v_add_f32_e32 v43, v223, v43
	v_pk_fma_f32 v[210:211], v[178:179], v[50:51], v[210:211] op_sel_hi:[0,1,1]
	v_pk_mul_f32 v[50:51], v[184:185], v[184:185]
	v_add_f32_e32 v43, v225, v43
	v_pk_mul_f32 v[212:213], v[210:211], v[210:211]
	v_add_f32_e32 v43, v43, v50
	v_add_f32_e32 v43, v212, v43
	v_add_f32_e32 v43, v51, v43
	v_add_f32_e32 v43, v213, v43
	v_add_f32_e32 v43, v221, v43
	v_add_f32_e32 v43, v220, v43
	v_add_f32_e32 v43, v53, v43
	v_add_f32_e32 v43, v52, v43
	ds_bpermute_b32 v50, v127, v43
	s_waitcnt lgkmcnt(0)
	v_add_f32_e32 v43, v43, v50
	ds_bpermute_b32 v50, v145, v43
	s_waitcnt lgkmcnt(0)
	v_add_f32_e32 v43, v43, v50
	ds_bpermute_b32 v50, v149, v43
	s_waitcnt lgkmcnt(0)
	v_add_f32_e32 v43, v43, v50
	v_fmamk_f32 v43, v43, 0x3c000000, v244
	v_cmp_gt_f32_e32 vcc, s3, v43
	v_mul_f32_e32 v50, 0x4f800000, v43
	s_nop 0
	v_cndmask_b32_e32 v43, v43, v50, vcc
	v_sqrt_f32_e32 v50, v43
	s_nop 0
	v_add_u32_e32 v51, -1, v50
	v_fma_f32 v52, -v51, v50, v43
	v_cmp_ge_f32_e64 s[4:5], 0, v52
	v_add_u32_e32 v52, 1, v50
	s_nop 0
	v_cndmask_b32_e64 v51, v50, v51, s[4:5]
	v_fma_f32 v50, -v52, v50, v43
	v_cmp_lt_f32_e64 s[4:5], 0, v50
	s_nop 1
	v_cndmask_b32_e64 v50, v51, v52, s[4:5]
	v_mul_f32_e32 v51, 0x37800000, v50
	v_cndmask_b32_e32 v50, v50, v51, vcc
	v_cmp_class_f32_e32 vcc, v43, v245
	s_nop 1
	v_cndmask_b32_e32 v43, v50, v43, vcc
	v_div_scale_f32 v50, s[0:1], v43, v43, 1.0
	v_rcp_f32_e32 v51, v50
	s_nop 0
	v_fma_f32 v52, -v50, v51, 1.0
	v_fmac_f32_e32 v51, v52, v51
	v_div_scale_f32 v52, vcc, 1.0, v43, 1.0
	v_mul_f32_e32 v53, v52, v51
	v_fma_f32 v178, -v50, v53, v52
	v_fmac_f32_e32 v53, v178, v51
	v_fma_f32 v50, -v50, v53, v52
	v_div_fmas_f32 v50, v50, v51, v53
	v_div_fixup_f32 v178, v50, v43, 1.0
	v_pk_mul_f32 v[50:51], v[178:179], v[54:55] op_sel_hi:[0,1]
	v_pk_mul_f32 v[54:55], v[178:179], v[56:57] op_sel_hi:[0,1]
	v_pk_mul_f32 v[10:11], v[178:179], v[10:11] op_sel_hi:[0,1]
	v_pk_mul_f32 v[50:51], v[50:51], v[236:237]
	v_pk_mul_f32 v[52:53], v[178:179], v[226:227] op_sel_hi:[0,1]
	v_pk_mul_f32 v[54:55], v[54:55], v[186:187]
	v_pk_mul_f32 v[10:11], v[10:11], v[64:65]
	v_pk_mul_f32 v[52:53], v[52:53], v[228:229]
	v_bfe_u32 v43, v55, 16, 1
	v_bfe_u32 v56, v54, 16, 1
	v_bfe_u32 v57, v51, 16, 1
	v_bfe_u32 v64, v50, 16, 1
	v_add3_u32 v50, v50, v64, s11
	v_add3_u32 v51, v51, v57, s11
	v_add3_u32 v54, v54, v56, s11
	v_add3_u32 v43, v55, v43, s11
	v_bfe_u32 v55, v10, 16, 1
	v_bfe_u32 v56, v11, 16, 1
	v_bfe_u32 v57, v52, 16, 1
	v_bfe_u32 v64, v53, 16, 1
	v_add3_u32 v53, v53, v64, s11
	v_add3_u32 v52, v52, v57, s11
	v_add3_u32 v11, v11, v56, s11
	v_add3_u32 v10, v10, v55, s11
	v_lshrrev_b32_e32 v10, 16, v10
	v_lshrrev_b32_e32 v11, 16, v11
	v_lshrrev_b32_e32 v52, 16, v52
	v_lshrrev_b32_e32 v53, 16, v53
	v_add_co_u32_e32 v6, vcc, s28, v6
	v_and_or_b32 v53, v43, s23, v53
	v_and_or_b32 v52, v54, s23, v52
	v_and_or_b32 v51, v51, s23, v11
	v_and_or_b32 v50, v50, s23, v10
	v_addc_co_u32_e32 v7, vcc, 0, v7, vcc
	global_store_dwordx4 v[6:7], v[50:53], off offset:2048
	ds_read_b128 v[50:53], v74 offset:48
	s_nop 0
	ds_read_b128 v[54:57], v74 offset:32
	v_pk_mul_f32 v[10:11], v[178:179], v[184:185] op_sel_hi:[0,1]
	s_waitcnt lgkmcnt(0)
; __device__ __forceinline__ float sx(float v, int mask, int lane) { return __int_as_float(__builtin_amdgcn_ds_bpermute((lane ^ mask) << 2, __float_as_int(v))); }
; __device__ __forceinline__ float bflo(unsigned w) { return __uint_as_float(w << 16); }
; __device__ __forceinline__ float bfhi(unsigned w) { return __uint_as_float(w & 0xffff0000u); }
; __device__ __forceinline__ unsigned pk2(float lo, float hi) { return f2bf(lo) | (f2bf(hi) << 16); }
; __device__ __forceinline__ void dil_combine_load(float (&o)[16], float& rn, const bf16_t* p0, const bf16_t* p1, const bf16_t* xo, const float* lse0, const float* lse1, const float* lse2, int lane) {
;     ...
;     for (int j = 0; j < 2; ++j) { const u32x4 a = *(const u32x4*)(p0 + off + 8 * j), bq = *(const u32x4*)(p1 + off + 8 * j), cq = *(const u32x4*)(xo + off + 8 * j);
; #pragma unroll
;         for (int e = 0; e < 4; ++e) { o[8 * j + 2 * e] = w0 * bflo(a[e]) + w1 * bflo(bq[e]) + w2 * bflo(cq[e]); o[8 * j + 2 * e + 1] = w0 * bfhi(a[e]) + w1 * bfhi(bq[e]) + w2 * bfhi(cq[e]); } }
; #pragma unroll
;     for (int d = 0; d < 16; ++d) ss += o[d] * o[d];
;     ss += sx(ss, 1, lane); ss += sx(ss, 2, lane); ss += sx(ss, 4, lane);
;     rn = 1.0f / sqrtf(ss * (1.f / 128.f) + RMS_EPS);
; }
; __device__ __forceinline__ void dil_combine_store(const float (&o)[16], float rn, bf16_t* xo, const float* g_dil, int lane) {
;     const int h = lane >> 3, seg = lane & 7; const int off = h * 128 + seg * 16;
; #pragma unroll
;     for (int j = 0; j < 2; ++j) { u32x4 w;
; #pragma unroll
;         for (int e = 0; e < 4; ++e) w[e] = pk2(o[8 * j + 2 * e] * rn * g_dil[seg * 16 + 8 * j + 2 * e], o[8 * j + 2 * e + 1] * rn * g_dil[seg * 16 + 8 * j + 2 * e + 1]);
;         *(u32x4*)(xo + off + 8 * j) = w; }
	v_mov_b32_e32 v64, v54
	v_mov_b32_e32 v65, v56
	v_pk_mul_f32 v[10:11], v[10:11], v[64:65]
	v_pk_mul_f32 v[64:65], v[178:179], v[210:211] op_sel_hi:[0,1]
	v_mov_b32_e32 v56, v55
	v_pk_mul_f32 v[54:55], v[64:65], v[56:57]
	v_mov_b32_e32 v56, v73
	v_mov_b32_e32 v73, v60
	v_mov_b32_e32 v57, v61
	v_mov_b32_e32 v65, v52
	v_pk_mul_f32 v[60:61], v[178:179], v[72:73] op_sel_hi:[0,1]
	v_mov_b32_e32 v52, v51
	v_pk_mul_f32 v[56:57], v[178:179], v[56:57] op_sel_hi:[0,1]
	v_mov_b32_e32 v64, v50
	v_pk_mul_f32 v[50:51], v[60:61], v[52:53]
	v_pk_mul_f32 v[56:57], v[56:57], v[64:65]
	v_bfe_u32 v43, v51, 16, 1
	v_bfe_u32 v52, v50, 16, 1
	v_bfe_u32 v53, v55, 16, 1
	v_bfe_u32 v60, v54, 16, 1
	v_add3_u32 v54, v54, v60, s11
	v_add3_u32 v55, v55, v53, s11
	v_add3_u32 v50, v50, v52, s11
	v_add3_u32 v43, v51, v43, s11
	v_bfe_u32 v51, v10, 16, 1
	v_bfe_u32 v52, v11, 16, 1
	v_bfe_u32 v53, v56, 16, 1
	v_bfe_u32 v60, v57, 16, 1
	v_add3_u32 v57, v57, v60, s11
	v_add3_u32 v53, v56, v53, s11
	v_add3_u32 v11, v11, v52, s11
	v_add3_u32 v10, v10, v51, s11
	v_lshrrev_b32_e32 v10, 16, v10
	v_lshrrev_b32_e32 v11, 16, v11
	v_lshrrev_b32_e32 v51, 16, v53
	v_lshrrev_b32_e32 v52, 16, v57
	v_and_or_b32 v53, v43, s23, v52
	v_and_or_b32 v52, v50, s23, v51
	v_and_or_b32 v51, v55, s23, v11
	v_and_or_b32 v50, v54, s23, v10
	v_pk_mul_f32 v[10:11], v[206:207], v[208:209] op_sel_hi:[1,0]
	global_store_dwordx4 v[6:7], v[50:53], off offset:2064
	v_and_b32_e32 v56, 0xffff0000, v44
	v_lshlrev_b32_e32 v57, 16, v48
	v_pk_mul_f32 v[50:51], v[10:11], v[230:231] op_sel:[1,0] op_sel_hi:[0,1]
	v_pk_fma_f32 v[50:51], v[10:11], v[232:233], v[50:51]
	v_lshlrev_b32_e32 v53, 16, v39
	v_lshlrev_b32_e32 v52, 16, v38
	v_pk_fma_f32 v[50:51], v[144:145], v[52:53], v[50:51] op_sel_hi:[0,1,1]
	v_pk_mul_f32 v[52:53], v[10:11], v[202:203] op_sel:[1,0] op_sel_hi:[0,1]
	v_pk_fma_f32 v[52:53], v[10:11], v[204:205], v[52:53]
	ds_read_b128 v[184:187], v74 offset:16
	ds_read_b128 v[202:205], v74
	v_and_b32_e32 v60, 0xffff0000, v48
	v_lshlrev_b32_e32 v61, 16, v44
	v_pk_mul_f32 v[56:57], v[10:11], v[56:57] op_sel:[1,0] op_sel_hi:[0,1]
	v_and_b32_e32 v39, 0xffff0000, v39
	v_and_b32_e32 v38, 0xffff0000, v38
	v_and_b32_e32 v64, 0xffff0000, v36
	v_lshlrev_b32_e32 v65, 16, v36
	v_pk_fma_f32 v[56:57], v[10:11], v[60:61], v[56:57]
	v_pk_fma_f32 v[38:39], v[144:145], v[38:39], v[52:53] op_sel_hi:[0,1,1]
	v_pk_fma_f32 v[56:57], v[144:145], v[64:65], v[56:57] op_sel_hi:[0,1,1]
	v_and_b32_e32 v64, 0xffff0000, v45
	v_lshlrev_b32_e32 v65, 16, v49
	v_pk_mul_f32 v[72:73], v[10:11], v[174:175] op_sel:[1,0] op_sel_hi:[0,1]
	v_pk_mul_f32 v[52:53], v[50:51], v[50:51]
	v_pk_mul_f32 v[54:55], v[38:39], v[38:39]
	v_and_b32_e32 v44, 0xffff0000, v49
	v_pk_mul_f32 v[48:49], v[10:11], v[64:65] op_sel:[1,0] op_sel_hi:[0,1]
	v_lshlrev_b32_e32 v65, 16, v41
	v_lshlrev_b32_e32 v64, 16, v40
	v_pk_fma_f32 v[72:73], v[10:11], v[176:177], v[72:73]
	v_add_f32_e32 v43, v52, v54
	v_pk_fma_f32 v[64:65], v[144:145], v[64:65], v[72:73] op_sel_hi:[0,1,1]
	v_pk_mul_f32 v[72:73], v[10:11], v[170:171] op_sel:[1,0] op_sel_hi:[0,1]
	v_and_b32_e32 v41, 0xffff0000, v41
	v_and_b32_e32 v40, 0xffff0000, v40
	v_pk_fma_f32 v[72:73], v[10:11], v[172:173], v[72:73]
	v_add_f32_e32 v43, v53, v43
	v_pk_fma_f32 v[40:41], v[144:145], v[40:41], v[72:73] op_sel_hi:[0,1,1]
	v_pk_mul_f32 v[72:73], v[64:65], v[64:65]
	v_add_f32_e32 v43, v55, v43
	v_pk_mul_f32 v[170:171], v[40:41], v[40:41]
	v_pk_mul_f32 v[166:167], v[10:11], v[166:167] op_sel:[1,0] op_sel_hi:[0,1]
	v_add_f32_e32 v43, v72, v43
	v_lshlrev_b32_e32 v45, 16, v45
	v_lshlrev_b32_e32 v175, 16, v35
	v_lshlrev_b32_e32 v174, 16, v34
	v_pk_fma_f32 v[166:167], v[10:11], v[168:169], v[166:167]
	v_pk_mul_f32 v[162:163], v[10:11], v[162:163] op_sel:[1,0] op_sel_hi:[0,1]
	v_add_f32_e32 v43, v170, v43
	v_pk_fma_f32 v[44:45], v[10:11], v[44:45], v[48:49]
	v_and_b32_e32 v35, 0xffff0000, v35
	v_and_b32_e32 v34, 0xffff0000, v34
	v_pk_fma_f32 v[166:167], v[144:145], v[174:175], v[166:167] op_sel_hi:[0,1,1]
	v_pk_fma_f32 v[10:11], v[10:11], v[164:165], v[162:163]
	v_add_f32_e32 v43, v73, v43
	v_pk_fma_f32 v[10:11], v[144:145], v[34:35], v[10:11] op_sel_hi:[0,1,1]
	v_pk_mul_f32 v[34:35], v[166:167], v[166:167]
	v_add_f32_e32 v43, v171, v43
	v_pk_mul_f32 v[162:163], v[10:11], v[10:11]
	v_add_f32_e32 v34, v43, v34
	v_add_f32_e32 v34, v162, v34
	v_add_f32_e32 v34, v35, v34
	v_pk_mul_f32 v[60:61], v[56:57], v[56:57]
	v_and_b32_e32 v36, 0xffff0000, v37
	v_lshlrev_b32_e32 v37, 16, v37
	v_add_f32_e32 v34, v163, v34
	v_pk_fma_f32 v[44:45], v[144:145], v[36:37], v[44:45] op_sel_hi:[0,1,1]
	v_add_f32_e32 v34, v61, v34
	v_pk_mul_f32 v[36:37], v[44:45], v[44:45]
	v_add_f32_e32 v34, v60, v34
	v_add_f32_e32 v34, v37, v34
	v_add_f32_e32 v34, v36, v34
	ds_bpermute_b32 v35, v127, v34
	v_lshl_add_u64 v[6:7], s[76:77], 0, v[118:119]
	v_lshl_add_u64 v[118:119], v[118:119], 0, s[30:31]
	s_waitcnt lgkmcnt(0)
	v_add_f32_e32 v34, v34, v35
	ds_bpermute_b32 v35, v145, v34
	s_waitcnt lgkmcnt(0)
	v_add_f32_e32 v34, v34, v35
	ds_bpermute_b32 v35, v149, v34
	s_waitcnt lgkmcnt(0)
	v_mov_b32_e32 v173, v186
	s_waitcnt lgkmcnt(0)
	v_add_f32_e32 v34, v34, v35
	v_fmamk_f32 v34, v34, 0x3c000000, v244
	v_cmp_gt_f32_e32 vcc, s3, v34
	v_mul_f32_e32 v35, 0x4f800000, v34
	s_waitcnt lgkmcnt(0)
; __device__ __forceinline__ float sx(float v, int mask, int lane) { return __int_as_float(__builtin_amdgcn_ds_bpermute((lane ^ mask) << 2, __float_as_int(v))); }
; __device__ __forceinline__ float bflo(unsigned w) { return __uint_as_float(w << 16); }
; __device__ __forceinline__ float bfhi(unsigned w) { return __uint_as_float(w & 0xffff0000u); }
; __device__ __forceinline__ unsigned pk2(float lo, float hi) { return f2bf(lo) | (f2bf(hi) << 16); }
; __device__ __forceinline__ void dil_combine_load(float (&o)[16], float& rn, const bf16_t* p0, const bf16_t* p1, const bf16_t* xo, const float* lse0, const float* lse1, const float* lse2, int lane) {
;     ...
;     for (int j = 0; j < 2; ++j) { const u32x4 a = *(const u32x4*)(p0 + off + 8 * j), bq = *(const u32x4*)(p1 + off + 8 * j), cq = *(const u32x4*)(xo + off + 8 * j);
; #pragma unroll
;         for (int e = 0; e < 4; ++e) { o[8 * j + 2 * e] = w0 * bflo(a[e]) + w1 * bflo(bq[e]) + w2 * bflo(cq[e]); o[8 * j + 2 * e + 1] = w0 * bfhi(a[e]) + w1 * bfhi(bq[e]) + w2 * bfhi(cq[e]); } }
; #pragma unroll
;     for (int d = 0; d < 16; ++d) ss += o[d] * o[d];
;     ss += sx(ss, 1, lane); ss += sx(ss, 2, lane); ss += sx(ss, 4, lane);
;     rn = 1.0f / sqrtf(ss * (1.f / 128.f) + RMS_EPS);
; }
; __device__ __forceinline__ void dil_combine_store(const float (&o)[16], float rn, bf16_t* xo, const float* g_dil, int lane) {
;     const int h = lane >> 3, seg = lane & 7; const int off = h * 128 + seg * 16;
; #pragma unroll
;     for (int j = 0; j < 2; ++j) { u32x4 w;
; #pragma unroll
;         for (int e = 0; e < 4; ++e) w[e] = pk2(o[8 * j + 2 * e] * rn * g_dil[seg * 16 + 8 * j + 2 * e], o[8 * j + 2 * e + 1] * rn * g_dil[seg * 16 + 8 * j + 2 * e + 1]);
;         *(u32x4*)(xo + off + 8 * j) = w; }
	v_mov_b32_e32 v49, v204
	v_cndmask_b32_e32 v34, v34, v35, vcc
	v_sqrt_f32_e32 v35, v34
	v_mov_b32_e32 v204, v203
	v_mov_b32_e32 v186, v185
	v_mov_b32_e32 v48, v202
	v_add_u32_e32 v36, -1, v35
	v_fma_f32 v37, -v36, v35, v34
	v_cmp_ge_f32_e64 s[4:5], 0, v37
	v_add_u32_e32 v37, 1, v35
	v_mov_b32_e32 v172, v184
	v_cndmask_b32_e64 v36, v35, v36, s[4:5]
	v_fma_f32 v35, -v37, v35, v34
	v_cmp_lt_f32_e64 s[4:5], 0, v35
	s_nop 1
	v_cndmask_b32_e64 v35, v36, v37, s[4:5]
	v_mul_f32_e32 v36, 0x37800000, v35
	v_cndmask_b32_e32 v35, v35, v36, vcc
	v_cmp_class_f32_e32 vcc, v34, v245
	s_nop 1
	v_cndmask_b32_e32 v34, v35, v34, vcc
	v_div_scale_f32 v35, s[0:1], v34, v34, 1.0
	v_rcp_f32_e32 v36, v35
	s_nop 0
	v_fma_f32 v37, -v35, v36, 1.0
	v_fmac_f32_e32 v36, v37, v36
	v_div_scale_f32 v37, vcc, 1.0, v34, 1.0
	v_mul_f32_e32 v43, v37, v36
	v_fma_f32 v52, -v35, v43, v37
	v_fmac_f32_e32 v43, v52, v36
	v_fma_f32 v35, -v35, v43, v37
	v_div_fmas_f32 v35, v35, v36, v43
	v_div_fixup_f32 v52, v35, v34, 1.0
	v_pk_mul_f32 v[36:37], v[52:53], v[38:39] op_sel_hi:[0,1]
	v_pk_mul_f32 v[40:41], v[52:53], v[40:41] op_sel_hi:[0,1]
	v_pk_mul_f32 v[34:35], v[52:53], v[50:51] op_sel_hi:[0,1]
	v_pk_mul_f32 v[36:37], v[36:37], v[204:205]
	v_pk_mul_f32 v[38:39], v[52:53], v[64:65] op_sel_hi:[0,1]
	v_pk_mul_f32 v[40:41], v[40:41], v[186:187]
	v_pk_mul_f32 v[34:35], v[34:35], v[48:49]
	v_pk_mul_f32 v[38:39], v[38:39], v[172:173]
	v_bfe_u32 v43, v41, 16, 1
	v_bfe_u32 v48, v40, 16, 1
	v_bfe_u32 v49, v37, 16, 1
	v_bfe_u32 v50, v36, 16, 1
	v_add3_u32 v50, v36, v50, s11
	v_add3_u32 v49, v37, v49, s11
	v_add3_u32 v36, v40, v48, s11
	v_add3_u32 v37, v41, v43, s11
	v_bfe_u32 v40, v34, 16, 1
	v_bfe_u32 v41, v35, 16, 1
	v_bfe_u32 v43, v38, 16, 1
	v_bfe_u32 v48, v39, 16, 1
	v_add3_u32 v39, v39, v48, s11
	v_add3_u32 v38, v38, v43, s11
	v_add3_u32 v35, v35, v41, s11
	v_add3_u32 v34, v34, v40, s11
	v_lshrrev_b32_e32 v34, 16, v34
	v_lshrrev_b32_e32 v35, 16, v35
	v_lshrrev_b32_e32 v38, 16, v38
	v_lshrrev_b32_e32 v39, 16, v39
	v_add_co_u32_e32 v6, vcc, s28, v6
	v_and_or_b32 v37, v37, s23, v39
	v_and_or_b32 v36, v36, s23, v38
	v_and_or_b32 v35, v49, s23, v35
	v_and_or_b32 v34, v50, s23, v34
	v_addc_co_u32_e32 v7, vcc, 0, v7, vcc
	global_store_dwordx4 v[6:7], v[34:37], off offset:2048
	ds_read_b128 v[34:37], v74 offset:48
	s_nop 0
	ds_read_b128 v[38:41], v74 offset:32
	v_pk_mul_f32 v[10:11], v[52:53], v[10:11] op_sel_hi:[0,1]
	v_pk_mul_f32 v[48:49], v[52:53], v[166:167] op_sel_hi:[0,1]
	s_waitcnt lgkmcnt(0)
	v_mov_b32_e32 v50, v38
	v_mov_b32_e32 v51, v40
	v_mov_b32_e32 v40, v39
	v_mov_b32_e32 v38, v57
	v_mov_b32_e32 v39, v45
	v_pk_mul_f32 v[10:11], v[10:11], v[40:41]
	v_pk_mul_f32 v[38:39], v[52:53], v[38:39] op_sel_hi:[0,1]
	v_mov_b32_e32 v40, v34
	v_mov_b32_e32 v41, v36
	v_mov_b32_e32 v57, v44
	v_pk_mul_f32 v[38:39], v[38:39], v[40:41]
	v_pk_mul_f32 v[40:41], v[52:53], v[56:57] op_sel_hi:[0,1]
	v_mov_b32_e32 v36, v35
	v_pk_mul_f32 v[34:35], v[40:41], v[36:37]
	v_pk_mul_f32 v[48:49], v[48:49], v[50:51]
	v_bfe_u32 v36, v35, 16, 1
	v_bfe_u32 v37, v34, 16, 1
	v_bfe_u32 v40, v11, 16, 1
	v_bfe_u32 v41, v10, 16, 1
	v_add3_u32 v10, v10, v41, s11
	v_add3_u32 v11, v11, v40, s11
	v_add3_u32 v34, v34, v37, s11
	v_add3_u32 v35, v35, v36, s11
	v_bfe_u32 v36, v48, 16, 1
	v_bfe_u32 v37, v49, 16, 1
	v_bfe_u32 v40, v38, 16, 1
	v_bfe_u32 v41, v39, 16, 1
	v_add3_u32 v39, v39, v41, s11
	v_add3_u32 v38, v38, v40, s11
	v_add3_u32 v37, v49, v37, s11
	v_add3_u32 v36, v48, v36, s11
	v_lshrrev_b32_e32 v40, 16, v36
	v_lshrrev_b32_e32 v41, 16, v37
	v_lshrrev_b32_e32 v36, 16, v38
	v_lshrrev_b32_e32 v37, 16, v39
	v_and_or_b32 v37, v35, s23, v37
	v_and_or_b32 v36, v34, s23, v36
	v_and_or_b32 v35, v11, s23, v41
	v_and_or_b32 v34, v10, s23, v40
	v_pk_mul_f32 v[10:11], v[146:147], v[148:149] op_sel_hi:[1,0]
	v_and_b32_e32 v40, 0xffff0000, v28
	v_lshlrev_b32_e32 v41, 16, v32
	v_and_b32_e32 v44, 0xffff0000, v32
	v_lshlrev_b32_e32 v45, 16, v28
	v_pk_mul_f32 v[40:41], v[10:11], v[40:41] op_sel:[1,0] op_sel_hi:[0,1]
	v_and_b32_e32 v48, 0xffff0000, v20
	v_lshlrev_b32_e32 v49, 16, v20
	v_pk_fma_f32 v[40:41], v[10:11], v[44:45], v[40:41]
	global_store_dwordx4 v[6:7], v[34:37], off offset:2064
	v_pk_fma_f32 v[40:41], v[42:43], v[48:49], v[40:41] op_sel_hi:[0,1,1]
	v_and_b32_e32 v48, 0xffff0000, v29
	v_lshlrev_b32_e32 v49, 16, v33
	v_and_b32_e32 v28, 0xffff0000, v33
	v_pk_mul_f32 v[32:33], v[10:11], v[48:49] op_sel:[1,0] op_sel_hi:[0,1]
	ds_read_b128 v[48:51], v74 offset:16
	ds_read_b128 v[52:55], v74
	v_pk_mul_f32 v[34:35], v[10:11], v[198:199] op_sel:[1,0] op_sel_hi:[0,1]
	v_pk_fma_f32 v[34:35], v[10:11], v[200:201], v[34:35]
	v_lshlrev_b32_e32 v37, 16, v23
	v_lshlrev_b32_e32 v36, 16, v22
	v_pk_fma_f32 v[34:35], v[42:43], v[36:37], v[34:35] op_sel_hi:[0,1,1]
	v_pk_mul_f32 v[36:37], v[10:11], v[150:151] op_sel:[1,0] op_sel_hi:[0,1]
	v_pk_fma_f32 v[36:37], v[10:11], v[152:153], v[36:37]
	v_and_b32_e32 v23, 0xffff0000, v23
	v_and_b32_e32 v22, 0xffff0000, v22
	v_pk_fma_f32 v[22:23], v[42:43], v[22:23], v[36:37] op_sel_hi:[0,1,1]
	v_lshlrev_b32_e32 v29, 16, v29
	v_pk_mul_f32 v[56:57], v[10:11], v[140:141] op_sel:[1,0] op_sel_hi:[0,1]
	v_pk_mul_f32 v[36:37], v[34:35], v[34:35]
	v_pk_mul_f32 v[38:39], v[22:23], v[22:23]
	v_pk_fma_f32 v[28:29], v[10:11], v[28:29], v[32:33]
	v_pk_fma_f32 v[56:57], v[10:11], v[142:143], v[56:57]
	v_add_f32_e32 v36, v36, v38
	v_add_f32_e32 v36, v37, v36
	v_pk_mul_f32 v[72:73], v[10:11], v[132:133] op_sel:[1,0] op_sel_hi:[0,1]
	v_add_f32_e32 v36, v39, v36
	v_pk_fma_f32 v[72:73], v[10:11], v[134:135], v[72:73]
	v_and_b32_e32 v20, 0xffff0000, v21
	v_lshlrev_b32_e32 v21, 16, v21
	v_pk_fma_f32 v[28:29], v[42:43], v[20:21], v[28:29] op_sel_hi:[0,1,1]
	v_pk_mul_f32 v[44:45], v[40:41], v[40:41]
	v_pk_mul_f32 v[20:21], v[28:29], v[28:29]
	v_lshl_add_u64 v[6:7], s[76:77], 0, v[110:111]
	v_lshl_add_u64 v[110:111], v[110:111], 0, s[30:31]
	s_waitcnt lgkmcnt(0)
; __device__ __forceinline__ float sx(float v, int mask, int lane) { return __int_as_float(__builtin_amdgcn_ds_bpermute((lane ^ mask) << 2, __float_as_int(v))); }
; __device__ __forceinline__ float bflo(unsigned w) { return __uint_as_float(w << 16); }
; __device__ __forceinline__ float bfhi(unsigned w) { return __uint_as_float(w & 0xffff0000u); }
; __device__ __forceinline__ unsigned pk2(float lo, float hi) { return f2bf(lo) | (f2bf(hi) << 16); }
; __device__ __forceinline__ void dil_combine_load(float (&o)[16], float& rn, const bf16_t* p0, const bf16_t* p1, const bf16_t* xo, const float* lse0, const float* lse1, const float* lse2, int lane) {
;     ...
;     for (int j = 0; j < 2; ++j) { const u32x4 a = *(const u32x4*)(p0 + off + 8 * j), bq = *(const u32x4*)(p1 + off + 8 * j), cq = *(const u32x4*)(xo + off + 8 * j);
; #pragma unroll
;         for (int e = 0; e < 4; ++e) { o[8 * j + 2 * e] = w0 * bflo(a[e]) + w1 * bflo(bq[e]) + w2 * bflo(cq[e]); o[8 * j + 2 * e + 1] = w0 * bfhi(a[e]) + w1 * bfhi(bq[e]) + w2 * bfhi(cq[e]); } }
; #pragma unroll
;     for (int d = 0; d < 16; ++d) ss += o[d] * o[d];
;     ss += sx(ss, 1, lane); ss += sx(ss, 2, lane); ss += sx(ss, 4, lane);
;     rn = 1.0f / sqrtf(ss * (1.f / 128.f) + RMS_EPS);
; }
; __device__ __forceinline__ void dil_combine_store(const float (&o)[16], float rn, bf16_t* xo, const float* g_dil, int lane) {
;     const int h = lane >> 3, seg = lane & 7; const int off = h * 128 + seg * 16;
; #pragma unroll
;     for (int j = 0; j < 2; ++j) { u32x4 w;
; #pragma unroll
;         for (int e = 0; e < 4; ++e) w[e] = pk2(o[8 * j + 2 * e] * rn * g_dil[seg * 16 + 8 * j + 2 * e], o[8 * j + 2 * e + 1] * rn * g_dil[seg * 16 + 8 * j + 2 * e + 1]);
;         *(u32x4*)(xo + off + 8 * j) = w; }
	v_mov_b32_e32 v64, v48
	s_waitcnt lgkmcnt(0)
	v_mov_b32_e32 v32, v52
	v_mov_b32_e32 v33, v54
	v_mov_b32_e32 v54, v53
	v_lshlrev_b32_e32 v53, 16, v25
	v_lshlrev_b32_e32 v52, 16, v24
	v_pk_fma_f32 v[52:53], v[42:43], v[52:53], v[56:57] op_sel_hi:[0,1,1]
	v_pk_mul_f32 v[56:57], v[10:11], v[136:137] op_sel:[1,0] op_sel_hi:[0,1]
	v_and_b32_e32 v25, 0xffff0000, v25
	v_and_b32_e32 v24, 0xffff0000, v24
	v_pk_fma_f32 v[56:57], v[10:11], v[138:139], v[56:57]
	v_mov_b32_e32 v65, v50
	v_pk_fma_f32 v[24:25], v[42:43], v[24:25], v[56:57] op_sel_hi:[0,1,1]
	v_pk_mul_f32 v[56:57], v[52:53], v[52:53]
	v_pk_mul_f32 v[60:61], v[24:25], v[24:25]
	v_mov_b32_e32 v50, v49
	v_lshlrev_b32_e32 v49, 16, v19
	v_lshlrev_b32_e32 v48, 16, v18
	v_add_f32_e32 v36, v56, v36
	v_pk_fma_f32 v[48:49], v[42:43], v[48:49], v[72:73] op_sel_hi:[0,1,1]
	v_pk_mul_f32 v[72:73], v[10:11], v[128:129] op_sel:[1,0] op_sel_hi:[0,1]
	v_add_f32_e32 v36, v60, v36
	v_and_b32_e32 v19, 0xffff0000, v19
	v_and_b32_e32 v18, 0xffff0000, v18
	v_pk_fma_f32 v[10:11], v[10:11], v[130:131], v[72:73]
	v_add_f32_e32 v36, v57, v36
	v_pk_fma_f32 v[10:11], v[42:43], v[18:19], v[10:11] op_sel_hi:[0,1,1]
	v_pk_mul_f32 v[18:19], v[48:49], v[48:49]
	v_add_f32_e32 v36, v61, v36
	v_pk_mul_f32 v[42:43], v[10:11], v[10:11]
	v_add_f32_e32 v18, v36, v18
	v_add_f32_e32 v18, v42, v18
	v_add_f32_e32 v18, v19, v18
	v_add_f32_e32 v18, v43, v18
	v_add_f32_e32 v18, v45, v18
	v_add_f32_e32 v18, v44, v18
	v_add_f32_e32 v18, v21, v18
	v_add_f32_e32 v18, v20, v18
	ds_bpermute_b32 v19, v127, v18
	s_waitcnt lgkmcnt(0)
	v_add_f32_e32 v18, v18, v19
	ds_bpermute_b32 v19, v145, v18
	s_waitcnt lgkmcnt(0)
	v_add_f32_e32 v18, v18, v19
	ds_bpermute_b32 v19, v149, v18
	s_waitcnt lgkmcnt(0)
	v_add_f32_e32 v18, v18, v19
	v_fmamk_f32 v18, v18, 0x3c000000, v244
	v_cmp_gt_f32_e32 vcc, s3, v18
	v_mul_f32_e32 v19, 0x4f800000, v18
	s_nop 0
	v_cndmask_b32_e32 v18, v18, v19, vcc
	v_sqrt_f32_e32 v19, v18
	s_nop 0
	v_add_u32_e32 v20, -1, v19
	v_fma_f32 v21, -v20, v19, v18
	v_cmp_ge_f32_e64 s[4:5], 0, v21
	v_add_u32_e32 v21, 1, v19
	s_nop 0
	v_cndmask_b32_e64 v20, v19, v20, s[4:5]
	v_fma_f32 v19, -v21, v19, v18
	v_cmp_lt_f32_e64 s[4:5], 0, v19
	s_nop 1
	v_cndmask_b32_e64 v19, v20, v21, s[4:5]
	v_mul_f32_e32 v20, 0x37800000, v19
	v_cndmask_b32_e32 v19, v19, v20, vcc
	v_cmp_class_f32_e32 vcc, v18, v245
	s_nop 1
	v_cndmask_b32_e32 v18, v19, v18, vcc
	v_div_scale_f32 v19, s[0:1], v18, v18, 1.0
	v_rcp_f32_e32 v20, v19
	s_nop 0
	v_fma_f32 v21, -v19, v20, 1.0
	v_fmac_f32_e32 v20, v21, v20
	v_div_scale_f32 v21, vcc, 1.0, v18, 1.0
	v_mul_f32_e32 v36, v21, v20
	v_fma_f32 v37, -v19, v36, v21
	v_fmac_f32_e32 v36, v37, v20
	v_fma_f32 v19, -v19, v36, v21
	v_div_fmas_f32 v19, v19, v20, v36
	v_div_fixup_f32 v36, v19, v18, 1.0
	v_pk_mul_f32 v[20:21], v[36:37], v[22:23] op_sel_hi:[0,1]
	v_pk_mul_f32 v[24:25], v[36:37], v[24:25] op_sel_hi:[0,1]
	v_pk_mul_f32 v[18:19], v[36:37], v[34:35] op_sel_hi:[0,1]
	v_pk_mul_f32 v[20:21], v[20:21], v[54:55]
	v_pk_mul_f32 v[22:23], v[36:37], v[52:53] op_sel_hi:[0,1]
	v_pk_mul_f32 v[24:25], v[24:25], v[50:51]
	v_pk_mul_f32 v[18:19], v[18:19], v[32:33]
	v_pk_mul_f32 v[22:23], v[22:23], v[64:65]
	v_bfe_u32 v32, v25, 16, 1
	v_bfe_u32 v33, v24, 16, 1
	v_bfe_u32 v34, v21, 16, 1
	v_bfe_u32 v35, v20, 16, 1
	v_add3_u32 v35, v20, v35, s11
	v_add3_u32 v34, v21, v34, s11
	v_add3_u32 v20, v24, v33, s11
	v_add3_u32 v21, v25, v32, s11
	v_bfe_u32 v24, v18, 16, 1
	v_bfe_u32 v25, v19, 16, 1
	v_bfe_u32 v32, v22, 16, 1
	v_bfe_u32 v33, v23, 16, 1
	v_add3_u32 v23, v23, v33, s11
	v_add3_u32 v22, v22, v32, s11
	v_add3_u32 v19, v19, v25, s11
	v_add3_u32 v18, v18, v24, s11
	v_lshrrev_b32_e32 v18, 16, v18
	v_lshrrev_b32_e32 v19, 16, v19
	v_lshrrev_b32_e32 v22, 16, v22
	v_lshrrev_b32_e32 v23, 16, v23
	v_add_co_u32_e32 v6, vcc, s28, v6
	v_and_or_b32 v21, v21, s23, v23
	v_and_or_b32 v20, v20, s23, v22
	v_and_or_b32 v19, v34, s23, v19
	v_and_or_b32 v18, v35, s23, v18
	v_addc_co_u32_e32 v7, vcc, 0, v7, vcc
	global_store_dwordx4 v[6:7], v[18:21], off offset:2048
	ds_read_b128 v[18:21], v74 offset:48
	s_nop 0
	ds_read_b128 v[22:25], v74 offset:32
	v_pk_mul_f32 v[10:11], v[36:37], v[10:11] op_sel_hi:[0,1]
	v_pk_mul_f32 v[32:33], v[36:37], v[48:49] op_sel_hi:[0,1]
	s_waitcnt lgkmcnt(0)
; __device__ __forceinline__ float sx(float v, int mask, int lane) { return __int_as_float(__builtin_amdgcn_ds_bpermute((lane ^ mask) << 2, __float_as_int(v))); }
; __device__ __forceinline__ float bflo(unsigned w) { return __uint_as_float(w << 16); }
; __device__ __forceinline__ float bfhi(unsigned w) { return __uint_as_float(w & 0xffff0000u); }
; __device__ __forceinline__ unsigned pk2(float lo, float hi) { return f2bf(lo) | (f2bf(hi) << 16); }
; __device__ __forceinline__ void dil_combine_load(float (&o)[16], float& rn, const bf16_t* p0, const bf16_t* p1, const bf16_t* xo, const float* lse0, const float* lse1, const float* lse2, int lane) {
;     ...
;     for (int j = 0; j < 2; ++j) { const u32x4 a = *(const u32x4*)(p0 + off + 8 * j), bq = *(const u32x4*)(p1 + off + 8 * j), cq = *(const u32x4*)(xo + off + 8 * j);
; #pragma unroll
;         for (int e = 0; e < 4; ++e) { o[8 * j + 2 * e] = w0 * bflo(a[e]) + w1 * bflo(bq[e]) + w2 * bflo(cq[e]); o[8 * j + 2 * e + 1] = w0 * bfhi(a[e]) + w1 * bfhi(bq[e]) + w2 * bfhi(cq[e]); } }
; #pragma unroll
;     for (int d = 0; d < 16; ++d) ss += o[d] * o[d];
;     ss += sx(ss, 1, lane); ss += sx(ss, 2, lane); ss += sx(ss, 4, lane);
;     rn = 1.0f / sqrtf(ss * (1.f / 128.f) + RMS_EPS);
; }
; __device__ __forceinline__ void dil_combine_store(const float (&o)[16], float rn, bf16_t* xo, const float* g_dil, int lane) {
;     const int h = lane >> 3, seg = lane & 7; const int off = h * 128 + seg * 16;
; #pragma unroll
;     for (int j = 0; j < 2; ++j) { u32x4 w;
; #pragma unroll
;         for (int e = 0; e < 4; ++e) w[e] = pk2(o[8 * j + 2 * e] * rn * g_dil[seg * 16 + 8 * j + 2 * e], o[8 * j + 2 * e + 1] * rn * g_dil[seg * 16 + 8 * j + 2 * e + 1]);
;         *(u32x4*)(xo + off + 8 * j) = w; }
	v_mov_b32_e32 v34, v22
	v_mov_b32_e32 v35, v24
	v_mov_b32_e32 v24, v23
	v_mov_b32_e32 v22, v41
	v_mov_b32_e32 v23, v29
	v_pk_mul_f32 v[10:11], v[10:11], v[24:25]
	v_pk_mul_f32 v[22:23], v[36:37], v[22:23] op_sel_hi:[0,1]
	v_mov_b32_e32 v24, v18
	v_mov_b32_e32 v25, v20
	v_mov_b32_e32 v41, v28
	v_pk_mul_f32 v[22:23], v[22:23], v[24:25]
	v_pk_mul_f32 v[24:25], v[36:37], v[40:41] op_sel_hi:[0,1]
	v_mov_b32_e32 v20, v19
	v_pk_mul_f32 v[18:19], v[24:25], v[20:21]
	v_pk_mul_f32 v[32:33], v[32:33], v[34:35]
	v_bfe_u32 v20, v19, 16, 1
	v_bfe_u32 v21, v18, 16, 1
	v_bfe_u32 v24, v11, 16, 1
	v_bfe_u32 v25, v10, 16, 1
	v_add3_u32 v10, v10, v25, s11
	v_add3_u32 v11, v11, v24, s11
	v_add3_u32 v18, v18, v21, s11
	v_add3_u32 v19, v19, v20, s11
	v_bfe_u32 v20, v32, 16, 1
	v_bfe_u32 v21, v33, 16, 1
	v_bfe_u32 v24, v22, 16, 1
	v_bfe_u32 v25, v23, 16, 1
	v_add3_u32 v23, v23, v25, s11
	v_add3_u32 v22, v22, v24, s11
	v_add3_u32 v21, v33, v21, s11
	v_add3_u32 v20, v32, v20, s11
	v_lshrrev_b32_e32 v24, 16, v20
	v_lshrrev_b32_e32 v25, 16, v21
	v_lshrrev_b32_e32 v20, 16, v22
	v_lshrrev_b32_e32 v21, 16, v23
	v_and_or_b32 v21, v19, s23, v21
	v_and_or_b32 v20, v18, s23, v20
	v_and_or_b32 v19, v11, s23, v25
	v_and_or_b32 v18, v10, s23, v24
	v_pk_mul_f32 v[10:11], v[124:125], v[126:127] op_sel_hi:[1,0]
	global_store_dwordx4 v[6:7], v[18:21], off offset:2064
	v_pk_mul_f32 v[6:7], v[10:11], v[158:159] op_sel:[1,0] op_sel_hi:[0,1]
	v_pk_fma_f32 v[6:7], v[10:11], v[160:161], v[6:7]
	v_lshlrev_b32_e32 v21, 16, v15
	v_lshlrev_b32_e32 v20, 16, v14
	v_pk_fma_f32 v[20:21], v[0:1], v[20:21], v[6:7] op_sel_hi:[0,1,1]
	v_pk_mul_f32 v[6:7], v[10:11], v[154:155] op_sel:[1,0] op_sel_hi:[0,1]
	v_pk_fma_f32 v[6:7], v[10:11], v[156:157], v[6:7]
	v_and_b32_e32 v15, 0xffff0000, v15
	v_and_b32_e32 v14, 0xffff0000, v14
	v_pk_fma_f32 v[14:15], v[0:1], v[14:15], v[6:7] op_sel_hi:[0,1,1]
	v_and_b32_e32 v6, 0xffff0000, v8
	v_lshlrev_b32_e32 v7, 16, v12
	v_and_b32_e32 v28, 0xffff0000, v12
	v_lshlrev_b32_e32 v29, 16, v8
	v_pk_mul_f32 v[6:7], v[10:11], v[6:7] op_sel:[1,0] op_sel_hi:[0,1]
	v_and_b32_e32 v32, 0xffff0000, v4
	v_lshlrev_b32_e32 v33, 16, v4
	v_pk_fma_f32 v[6:7], v[10:11], v[28:29], v[6:7]
	v_and_b32_e32 v8, 0xffff0000, v13
	v_pk_fma_f32 v[6:7], v[0:1], v[32:33], v[6:7] op_sel_hi:[0,1,1]
	v_and_b32_e32 v32, 0xffff0000, v9
	v_lshlrev_b32_e32 v33, 16, v13
	v_pk_mul_f32 v[12:13], v[10:11], v[32:33] op_sel:[1,0] op_sel_hi:[0,1]
	ds_read_b128 v[32:35], v74 offset:16
	ds_read_b128 v[36:39], v74
	v_lshlrev_b32_e32 v9, 16, v9
	v_pk_fma_f32 v[8:9], v[10:11], v[8:9], v[12:13]
	v_lshlrev_b32_e32 v13, 16, v17
	v_lshlrev_b32_e32 v12, 16, v16
	v_and_b32_e32 v17, 0xffff0000, v17
	v_and_b32_e32 v16, 0xffff0000, v16
	v_pk_mul_f32 v[22:23], v[20:21], v[20:21]
	v_pk_mul_f32 v[24:25], v[14:15], v[14:15]
	v_and_b32_e32 v4, 0xffff0000, v5
	v_lshlrev_b32_e32 v5, 16, v5
	v_pk_fma_f32 v[8:9], v[0:1], v[4:5], v[8:9] op_sel_hi:[0,1,1]
	v_pk_mul_f32 v[28:29], v[6:7], v[6:7]
	v_pk_mul_f32 v[4:5], v[8:9], v[8:9]
	v_lshl_add_u64 v[18:19], s[76:77], 0, v[102:103]
	v_lshl_add_u64 v[102:103], v[102:103], 0, s[30:31]
	s_waitcnt lgkmcnt(0)
	v_mov_b32_e32 v42, v32
	s_waitcnt lgkmcnt(0)
	v_mov_b32_e32 v40, v36
	v_mov_b32_e32 v41, v38
	v_mov_b32_e32 v38, v37
	v_pk_mul_f32 v[36:37], v[10:11], v[46:47] op_sel:[1,0] op_sel_hi:[0,1]
	v_pk_fma_f32 v[36:37], v[10:11], v[58:59], v[36:37]
	v_mov_b32_e32 v43, v34
	v_pk_fma_f32 v[36:37], v[0:1], v[12:13], v[36:37] op_sel_hi:[0,1,1]
	v_pk_mul_f32 v[12:13], v[10:11], v[26:27] op_sel:[1,0] op_sel_hi:[0,1]
	v_pk_fma_f32 v[12:13], v[10:11], v[30:31], v[12:13]
	v_mov_b32_e32 v34, v33
	v_pk_mul_f32 v[32:33], v[10:11], v[68:69] op_sel:[1,0] op_sel_hi:[0,1]
	v_pk_fma_f32 v[16:17], v[0:1], v[16:17], v[12:13] op_sel_hi:[0,1,1]
	v_lshlrev_b32_e32 v13, 16, v3
	v_lshlrev_b32_e32 v12, 16, v2
	v_pk_fma_f32 v[32:33], v[10:11], v[70:71], v[32:33]
	v_and_b32_e32 v3, 0xffff0000, v3
	v_pk_fma_f32 v[12:13], v[0:1], v[12:13], v[32:33] op_sel_hi:[0,1,1]
	v_pk_mul_f32 v[32:33], v[10:11], v[62:63] op_sel:[1,0] op_sel_hi:[0,1]
	v_and_b32_e32 v2, 0xffff0000, v2
	v_pk_fma_f32 v[10:11], v[10:11], v[66:67], v[32:33]
	v_pk_mul_f32 v[26:27], v[36:37], v[36:37]
	v_pk_fma_f32 v[10:11], v[0:1], v[2:3], v[10:11] op_sel_hi:[0,1,1]
	v_add_f32_e32 v0, v22, v24
	v_add_f32_e32 v0, v23, v0
	v_add_f32_e32 v0, v25, v0
	v_pk_mul_f32 v[30:31], v[16:17], v[16:17]
	v_add_f32_e32 v0, v26, v0
	v_add_f32_e32 v0, v30, v0
	v_add_f32_e32 v0, v27, v0
	v_pk_mul_f32 v[2:3], v[12:13], v[12:13]
	v_add_f32_e32 v0, v31, v0
	v_pk_mul_f32 v[32:33], v[10:11], v[10:11]
	v_add_f32_e32 v0, v0, v2
	v_add_f32_e32 v0, v32, v0
	v_add_f32_e32 v0, v3, v0
	v_add_f32_e32 v0, v33, v0
	v_add_f32_e32 v0, v29, v0
	v_add_f32_e32 v0, v28, v0
	v_add_f32_e32 v0, v5, v0
	v_add_f32_e32 v0, v4, v0
	ds_bpermute_b32 v2, v127, v0
	s_waitcnt lgkmcnt(0)
; __device__ __forceinline__ float sx(float v, int mask, int lane) { return __int_as_float(__builtin_amdgcn_ds_bpermute((lane ^ mask) << 2, __float_as_int(v))); }
; __device__ __forceinline__ float bflo(unsigned w) { return __uint_as_float(w << 16); }
; __device__ __forceinline__ float bfhi(unsigned w) { return __uint_as_float(w & 0xffff0000u); }
; __device__ __forceinline__ unsigned pk2(float lo, float hi) { return f2bf(lo) | (f2bf(hi) << 16); }
; __device__ __forceinline__ void dil_combine_load(float (&o)[16], float& rn, const bf16_t* p0, const bf16_t* p1, const bf16_t* xo, const float* lse0, const float* lse1, const float* lse2, int lane) {
;     ...
;     for (int j = 0; j < 2; ++j) { const u32x4 a = *(const u32x4*)(p0 + off + 8 * j), bq = *(const u32x4*)(p1 + off + 8 * j), cq = *(const u32x4*)(xo + off + 8 * j);
; #pragma unroll
;         for (int e = 0; e < 4; ++e) { o[8 * j + 2 * e] = w0 * bflo(a[e]) + w1 * bflo(bq[e]) + w2 * bflo(cq[e]); o[8 * j + 2 * e + 1] = w0 * bfhi(a[e]) + w1 * bfhi(bq[e]) + w2 * bfhi(cq[e]); } }
; #pragma unroll
;     for (int d = 0; d < 16; ++d) ss += o[d] * o[d];
;     ss += sx(ss, 1, lane); ss += sx(ss, 2, lane); ss += sx(ss, 4, lane);
;     rn = 1.0f / sqrtf(ss * (1.f / 128.f) + RMS_EPS);
; }
; __device__ __forceinline__ void dil_combine_store(const float (&o)[16], float rn, bf16_t* xo, const float* g_dil, int lane) {
;     const int h = lane >> 3, seg = lane & 7; const int off = h * 128 + seg * 16;
; #pragma unroll
;     for (int j = 0; j < 2; ++j) { u32x4 w;
; #pragma unroll
;         for (int e = 0; e < 4; ++e) w[e] = pk2(o[8 * j + 2 * e] * rn * g_dil[seg * 16 + 8 * j + 2 * e], o[8 * j + 2 * e + 1] * rn * g_dil[seg * 16 + 8 * j + 2 * e + 1]);
;         *(u32x4*)(xo + off + 8 * j) = w; }
	v_add_f32_e32 v0, v0, v2
	ds_bpermute_b32 v2, v145, v0
	s_waitcnt lgkmcnt(0)
	v_add_f32_e32 v0, v0, v2
	ds_bpermute_b32 v2, v149, v0
	s_waitcnt lgkmcnt(0)
	v_add_f32_e32 v0, v0, v2
	v_fmamk_f32 v0, v0, 0x3c000000, v244
	v_cmp_gt_f32_e32 vcc, s3, v0
	v_mul_f32_e32 v2, 0x4f800000, v0
	s_nop 0
	v_cndmask_b32_e32 v0, v0, v2, vcc
	v_sqrt_f32_e32 v2, v0
	s_nop 0
	v_add_u32_e32 v3, -1, v2
	v_fma_f32 v4, -v3, v2, v0
	v_cmp_ge_f32_e64 s[4:5], 0, v4
	v_add_u32_e32 v4, 1, v2
	s_nop 0
	v_cndmask_b32_e64 v3, v2, v3, s[4:5]
	v_fma_f32 v2, -v4, v2, v0
	v_cmp_lt_f32_e64 s[4:5], 0, v2
	s_nop 1
	v_cndmask_b32_e64 v2, v3, v4, s[4:5]
	v_mul_f32_e32 v3, 0x37800000, v2
	v_cndmask_b32_e32 v2, v2, v3, vcc
	v_cmp_class_f32_e32 vcc, v0, v245
	s_nop 1
	v_cndmask_b32_e32 v0, v2, v0, vcc
	v_div_scale_f32 v2, s[0:1], v0, v0, 1.0
	v_rcp_f32_e32 v3, v2
	s_nop 0
	v_fma_f32 v4, -v2, v3, 1.0
	v_fmac_f32_e32 v3, v4, v3
	v_div_scale_f32 v4, vcc, 1.0, v0, 1.0
	v_mul_f32_e32 v5, v4, v3
	v_fma_f32 v22, -v2, v5, v4
	v_fmac_f32_e32 v5, v22, v3
	v_fma_f32 v2, -v2, v5, v4
	v_div_fmas_f32 v2, v2, v3, v5
	v_div_fixup_f32 v0, v2, v0, 1.0
	v_pk_mul_f32 v[4:5], v[0:1], v[14:15] op_sel_hi:[0,1]
	v_pk_mul_f32 v[16:17], v[0:1], v[16:17] op_sel_hi:[0,1]
	v_pk_mul_f32 v[4:5], v[4:5], v[38:39]
	v_pk_mul_f32 v[14:15], v[0:1], v[36:37] op_sel_hi:[0,1]
	v_pk_mul_f32 v[16:17], v[16:17], v[34:35]
	v_pk_mul_f32 v[2:3], v[0:1], v[20:21] op_sel_hi:[0,1]
	v_pk_mul_f32 v[14:15], v[14:15], v[42:43]
	v_bfe_u32 v20, v17, 16, 1
	v_bfe_u32 v22, v5, 16, 1
	v_pk_mul_f32 v[2:3], v[2:3], v[40:41]
	v_bfe_u32 v21, v16, 16, 1
	v_bfe_u32 v23, v4, 16, 1
	v_add3_u32 v22, v5, v22, s11
	v_add3_u32 v5, v17, v20, s11
	v_bfe_u32 v20, v14, 16, 1
	v_add3_u32 v23, v4, v23, s11
	v_add3_u32 v4, v16, v21, s11
	v_bfe_u32 v16, v2, 16, 1
	v_bfe_u32 v17, v3, 16, 1
	v_bfe_u32 v21, v15, 16, 1
	v_add3_u32 v14, v14, v20, s11
	v_add3_u32 v15, v15, v21, s11
	v_add3_u32 v3, v3, v17, s11
	v_add3_u32 v2, v2, v16, s11
	v_lshrrev_b32_e32 v14, 16, v14
	v_lshrrev_b32_e32 v2, 16, v2
	v_lshrrev_b32_e32 v3, 16, v3
	v_lshrrev_b32_e32 v15, 16, v15
	v_and_or_b32 v4, v4, s23, v14
	v_add_co_u32_e32 v14, vcc, s28, v18
	v_and_or_b32 v5, v5, s23, v15
	v_and_or_b32 v3, v22, s23, v3
	v_and_or_b32 v2, v23, s23, v2
	v_addc_co_u32_e32 v15, vcc, 0, v19, vcc
	global_store_dwordx4 v[14:15], v[2:5], off offset:2048
	ds_read_b128 v[2:5], v74 offset:48
	s_nop 0
	ds_read_b128 v[16:19], v74 offset:32
	v_pk_mul_f32 v[10:11], v[0:1], v[10:11] op_sel_hi:[0,1]
	v_pk_mul_f32 v[12:13], v[0:1], v[12:13] op_sel_hi:[0,1]
	s_waitcnt lgkmcnt(0)
	v_mov_b32_e32 v20, v16
	v_mov_b32_e32 v21, v18
	v_mov_b32_e32 v18, v17
	v_mov_b32_e32 v16, v7
	v_mov_b32_e32 v7, v8
	v_pk_mul_f32 v[10:11], v[10:11], v[18:19]
	v_mov_b32_e32 v17, v9
	v_mov_b32_e32 v19, v4
	v_pk_mul_f32 v[6:7], v[0:1], v[6:7] op_sel_hi:[0,1]
	v_mov_b32_e32 v4, v3
	v_pk_mul_f32 v[16:17], v[0:1], v[16:17] op_sel_hi:[0,1]
	v_mov_b32_e32 v18, v2
	v_pk_mul_f32 v[2:3], v[6:7], v[4:5]
	v_pk_mul_f32 v[12:13], v[12:13], v[20:21]
	v_pk_mul_f32 v[16:17], v[16:17], v[18:19]
	v_bfe_u32 v0, v3, 16, 1
	v_bfe_u32 v4, v2, 16, 1
	v_bfe_u32 v5, v11, 16, 1
	v_add3_u32 v7, v11, v5, s11
	v_add3_u32 v2, v2, v4, s11
	v_add3_u32 v0, v3, v0, s11
	v_bfe_u32 v3, v12, 16, 1
	v_bfe_u32 v4, v13, 16, 1
	v_bfe_u32 v5, v16, 16, 1
	v_bfe_u32 v8, v17, 16, 1
	v_bfe_u32 v6, v10, 16, 1
	v_add3_u32 v8, v17, v8, s11
	v_add3_u32 v5, v16, v5, s11
	v_add3_u32 v4, v13, v4, s11
	v_add3_u32 v3, v12, v3, s11
	v_add3_u32 v6, v10, v6, s11
	v_lshrrev_b32_e32 v9, 16, v3
	v_lshrrev_b32_e32 v3, 16, v4
	v_lshrrev_b32_e32 v4, 16, v5
	v_lshrrev_b32_e32 v5, 16, v8
	v_and_or_b32 v5, v0, s23, v5
	v_and_or_b32 v4, v2, s23, v4
	v_and_or_b32 v3, v7, s23, v3
	v_and_or_b32 v2, v6, s23, v9
	global_store_dwordx4 v[14:15], v[2:5], off offset:2064
	s_cbranch_scc0 .LBB0_409
